# attention OA/OB bf16 output stores write-through (sc1)
# baseline (speedup 1.0000x reference)
.LBB0_186:
	v_and_b32_e32 v2, 64, v203
	v_xor_b32_e32 v1, 32, v203
	v_add_u32_e32 v2, 64, v2
	v_cmp_lt_i32_e32 vcc, v1, v2
	s_lshl_b32 s4, s3, 7
	s_nop 0
	v_cndmask_b32_e32 v1, v203, v1, vcc
	v_lshlrev_b32_e32 v1, 2, v1
	ds_bpermute_b32 v1, v1, v48
	s_waitcnt lgkmcnt(0)
	v_add_f32_e32 v1, v48, v1
	v_div_scale_f32 v2, s[0:1], v1, v1, 1.0
	v_rcp_f32_e32 v3, v2
	v_readlane_b32 s0, v253, 27
	v_readlane_b32 s1, v253, 28
	v_fma_f32 v4, -v2, v3, 1.0
	v_fmac_f32_e32 v3, v4, v3
	v_div_scale_f32 v4, vcc, 1.0, v1, 1.0
	v_mul_f32_e32 v5, v4, v3
	v_fma_f32 v6, -v2, v5, v4
	v_fmac_f32_e32 v5, v6, v3
	v_fma_f32 v2, -v2, v5, v4
	v_div_fmas_f32 v2, v2, v3, v5
	v_mov_b64_e32 v[4:5], s[0:1]
	v_div_fixup_f32 v2, v2, v1, 1.0
	v_mad_i64_i32 v[4:5], s[0:1], v194, s19, v[4:5]
	v_lshl_add_u64 v[4:5], v[4:5], 0, s[4:5]
	v_pk_mul_f32 v[6:7], v[32:33], v[2:3] op_sel_hi:[1,0]
	v_pk_mul_f32 v[8:9], v[34:35], v[2:3] op_sel_hi:[1,0]
	v_lshl_add_u64 v[4:5], v[178:179], 1, v[4:5]
	v_cvt_pk_bf16_f32 v6, v6, v7
	v_cvt_pk_bf16_f32 v7, v8, v9
	global_store_dwordx2 v[4:5], v[6:7], off sc1
	v_pk_mul_f32 v[6:7], v[36:37], v[2:3] op_sel_hi:[1,0]
	v_pk_mul_f32 v[8:9], v[38:39], v[2:3] op_sel_hi:[1,0]
	v_cvt_pk_bf16_f32 v6, v6, v7
	v_cvt_pk_bf16_f32 v7, v8, v9
	global_store_dwordx2 v[4:5], v[6:7], off offset:16 sc1
	v_pk_mul_f32 v[6:7], v[40:41], v[2:3] op_sel_hi:[1,0]
	v_pk_mul_f32 v[8:9], v[42:43], v[2:3] op_sel_hi:[1,0]
	v_cvt_pk_bf16_f32 v6, v6, v7
	v_cvt_pk_bf16_f32 v7, v8, v9
	global_store_dwordx2 v[4:5], v[6:7], off offset:32 sc1
	v_pk_mul_f32 v[6:7], v[44:45], v[2:3] op_sel_hi:[1,0]
	v_pk_mul_f32 v[8:9], v[46:47], v[2:3] op_sel_hi:[1,0]
	v_cvt_pk_bf16_f32 v6, v6, v7
	v_cvt_pk_bf16_f32 v7, v8, v9
	global_store_dwordx2 v[4:5], v[6:7], off offset:48 sc1
	v_pk_mul_f32 v[6:7], v[16:17], v[2:3] op_sel_hi:[1,0]
	v_pk_mul_f32 v[8:9], v[18:19], v[2:3] op_sel_hi:[1,0]
	v_cvt_pk_bf16_f32 v6, v6, v7
	v_cvt_pk_bf16_f32 v7, v8, v9
	global_store_dwordx2 v[4:5], v[6:7], off offset:64 sc1
	v_pk_mul_f32 v[6:7], v[20:21], v[2:3] op_sel_hi:[1,0]
	v_pk_mul_f32 v[8:9], v[22:23], v[2:3] op_sel_hi:[1,0]
	v_cvt_pk_bf16_f32 v6, v6, v7
	v_cvt_pk_bf16_f32 v7, v8, v9
	global_store_dwordx2 v[4:5], v[6:7], off offset:80 sc1
	v_pk_mul_f32 v[6:7], v[24:25], v[2:3] op_sel_hi:[1,0]
	v_pk_mul_f32 v[8:9], v[26:27], v[2:3] op_sel_hi:[1,0]
	v_cvt_pk_bf16_f32 v6, v6, v7
	v_cvt_pk_bf16_f32 v7, v8, v9
	global_store_dwordx2 v[4:5], v[6:7], off offset:96 sc1
	v_pk_mul_f32 v[6:7], v[28:29], v[2:3] op_sel_hi:[1,0]
	v_pk_mul_f32 v[2:3], v[30:31], v[2:3] op_sel_hi:[1,0]
	v_cvt_pk_bf16_f32 v6, v6, v7
	v_cvt_pk_bf16_f32 v7, v2, v3
	global_store_dwordx2 v[4:5], v[6:7], off offset:112 sc1
	s_waitcnt lgkmcnt(0)
	s_branch .LBB0_145

.LBB0_242:
	v_div_scale_f32 v2, s[20:21], v1, v1, 1.0
	v_rcp_f32_e32 v3, v2
	v_div_scale_f32 v4, vcc, 1.0, v1, 1.0
	v_fma_f32 v5, -v2, v3, 1.0
	v_fmac_f32_e32 v3, v5, v3
	v_mul_f32_e32 v5, v4, v3
	v_fma_f32 v6, -v2, v5, v4
	v_fmac_f32_e32 v5, v6, v3
	v_fma_f32 v2, -v2, v5, v4
	v_div_fmas_f32 v2, v2, v3, v5
	v_div_fixup_f32 v2, v2, v1, 1.0
	v_pk_mul_f32 v[6:7], v[32:33], v[2:3] op_sel_hi:[1,0]
	v_pk_mul_f32 v[8:9], v[34:35], v[2:3] op_sel_hi:[1,0]
	v_mad_i64_i32 v[4:5], s[20:21], v196, s19, v[190:191]
	v_cvt_pk_bf16_f32 v6, v6, v7
	v_cvt_pk_bf16_f32 v7, v8, v9
	global_store_dwordx2 v[4:5], v[6:7], off offset:1024 sc1
	v_pk_mul_f32 v[6:7], v[36:37], v[2:3] op_sel_hi:[1,0]
	v_pk_mul_f32 v[8:9], v[38:39], v[2:3] op_sel_hi:[1,0]
	v_cvt_pk_bf16_f32 v6, v6, v7
	v_cvt_pk_bf16_f32 v7, v8, v9
	global_store_dwordx2 v[4:5], v[6:7], off offset:1040 sc1
	v_pk_mul_f32 v[6:7], v[40:41], v[2:3] op_sel_hi:[1,0]
	v_pk_mul_f32 v[8:9], v[42:43], v[2:3] op_sel_hi:[1,0]
	v_cvt_pk_bf16_f32 v6, v6, v7
	v_cvt_pk_bf16_f32 v7, v8, v9
	global_store_dwordx2 v[4:5], v[6:7], off offset:1056 sc1
	v_pk_mul_f32 v[6:7], v[44:45], v[2:3] op_sel_hi:[1,0]
	v_pk_mul_f32 v[8:9], v[46:47], v[2:3] op_sel_hi:[1,0]
	v_cvt_pk_bf16_f32 v6, v6, v7
	v_cvt_pk_bf16_f32 v7, v8, v9
	global_store_dwordx2 v[4:5], v[6:7], off offset:1072 sc1
	v_pk_mul_f32 v[6:7], v[16:17], v[2:3] op_sel_hi:[1,0]
	v_pk_mul_f32 v[8:9], v[18:19], v[2:3] op_sel_hi:[1,0]
	v_cvt_pk_bf16_f32 v6, v6, v7
	v_cvt_pk_bf16_f32 v7, v8, v9
	global_store_dwordx2 v[4:5], v[6:7], off offset:1088 sc1
	v_pk_mul_f32 v[6:7], v[20:21], v[2:3] op_sel_hi:[1,0]
	v_pk_mul_f32 v[8:9], v[22:23], v[2:3] op_sel_hi:[1,0]
	v_cvt_pk_bf16_f32 v6, v6, v7
	v_cvt_pk_bf16_f32 v7, v8, v9
	global_store_dwordx2 v[4:5], v[6:7], off offset:1104 sc1
	v_pk_mul_f32 v[6:7], v[24:25], v[2:3] op_sel_hi:[1,0]
	v_pk_mul_f32 v[8:9], v[26:27], v[2:3] op_sel_hi:[1,0]
	v_cvt_pk_bf16_f32 v6, v6, v7
	v_cvt_pk_bf16_f32 v7, v8, v9
	global_store_dwordx2 v[4:5], v[6:7], off offset:1120 sc1
	v_pk_mul_f32 v[6:7], v[28:29], v[2:3] op_sel_hi:[1,0]
	v_pk_mul_f32 v[2:3], v[30:31], v[2:3] op_sel_hi:[1,0]
	v_cvt_pk_bf16_f32 v6, v6, v7
	v_cvt_pk_bf16_f32 v7, v2, v3
	global_store_dwordx2 v[4:5], v[6:7], off offset:1136 sc1
	s_branch .LBB0_202
